# attention row-max tree 11 ops -> 4 ops (scores never NaN)
# speedup vs baseline: 1.0135x; 1.0135x over previous
.LBB0_308:
	v_max3_f32 v162, v206, v208, v207
	v_max3_f32 v163, v209, v189, v212
	v_max_f32_e32 v164, v211, v210
	v_max3_f32 v162, v162, v163, v164
	ds_bpermute_b32 v163, v171, v162
	s_waitcnt lgkmcnt(0)
	v_max_f32_e32 v162, v162, v163
	ds_bpermute_b32 v163, v199, v162
	s_waitcnt lgkmcnt(0)
	v_max3_f32 v167, v203, v162, v163
	v_sub_f32_e32 v166, v209, v167
	v_mul_f32_e32 v166, 0x3fb8aa3b, v166
	v_exp_f32_e32 v168, v166
	v_sub_f32_e32 v166, v207, v167
	v_mul_f32_e32 v166, 0x3fb8aa3b, v166
	v_sub_f32_e32 v163, v208, v167
	v_exp_f32_e32 v169, v166
	v_sub_f32_e32 v166, v211, v167
	v_mul_f32_e32 v163, 0x3fb8aa3b, v163
	v_sub_f32_e32 v165, v206, v167
	v_mul_f32_e32 v166, 0x3fb8aa3b, v166
	v_sub_f32_e32 v162, v203, v167
	v_exp_f32_e32 v163, v163
	v_mul_f32_e32 v165, 0x3fb8aa3b, v165
	v_exp_f32_e32 v203, v166
	v_sub_f32_e32 v166, v210, v167
	v_exp_f32_e32 v165, v165
	v_mul_f32_e32 v166, 0x3fb8aa3b, v166
	v_exp_f32_e32 v206, v166
	v_sub_f32_e32 v166, v212, v167
	v_mul_f32_e32 v166, 0x3fb8aa3b, v166
	v_add_f32_e32 v164, 0, v163
	v_exp_f32_e32 v207, v166
	v_sub_f32_e32 v166, v189, v167
	v_mul_f32_e32 v162, 0x3fb8aa3b, v162
	v_add_f32_e32 v164, v165, v164
	v_mul_f32_e32 v166, 0x3fb8aa3b, v166
	v_add_f32_e32 v164, v168, v164
	v_exp_f32_e32 v189, v166
	v_exp_f32_e32 v166, v162
	v_add_f32_e32 v164, v169, v164
	v_add_f32_e32 v164, v203, v164
	v_add_f32_e32 v164, v206, v164
	v_add_f32_e32 v164, v207, v164
	v_pk_mul_f32 v[92:93], v[92:93], v[166:167] op_sel_hi:[1,0]
	v_pk_mul_f32 v[90:91], v[90:91], v[166:167] op_sel_hi:[1,0]
	v_pk_mul_f32 v[76:77], v[76:77], v[166:167] op_sel_hi:[1,0]
	v_pk_mul_f32 v[74:75], v[74:75], v[166:167] op_sel_hi:[1,0]
	v_pk_mul_f32 v[72:73], v[72:73], v[166:167] op_sel_hi:[1,0]
	v_pk_mul_f32 v[70:71], v[70:71], v[166:167] op_sel_hi:[1,0]
	v_pk_mul_f32 v[64:65], v[64:65], v[166:167] op_sel_hi:[1,0]
	v_pk_mul_f32 v[62:63], v[62:63], v[166:167] op_sel_hi:[1,0]
	v_pk_mul_f32 v[48:49], v[48:49], v[166:167] op_sel_hi:[1,0]
	v_pk_mul_f32 v[46:47], v[46:47], v[166:167] op_sel_hi:[1,0]
	v_pk_mul_f32 v[44:45], v[44:45], v[166:167] op_sel_hi:[1,0]
	v_pk_mul_f32 v[42:43], v[42:43], v[166:167] op_sel_hi:[1,0]
	v_pk_mul_f32 v[40:41], v[40:41], v[166:167] op_sel_hi:[1,0]
	v_pk_mul_f32 v[38:39], v[38:39], v[166:167] op_sel_hi:[1,0]
	v_pk_mul_f32 v[36:37], v[36:37], v[166:167] op_sel_hi:[1,0]
	v_pk_mul_f32 v[34:35], v[34:35], v[166:167] op_sel_hi:[1,0]
	v_add_f32_e32 v208, v189, v164
	v_cvt_pk_bf16_f32 v162, v163, v165
	v_cvt_pk_bf16_f32 v163, v168, v169
	v_cvt_pk_bf16_f32 v164, v203, v206
	v_cvt_pk_bf16_f32 v165, v207, v189
	v_fmac_f32_e32 v208, v201, v166
	v_mfma_f32_16x16x32_bf16 v[90:93], v[126:129], v[162:165], v[90:93]
	v_mov_b32_e32 v201, v208
	v_mov_b32_e32 v203, v167
	v_mfma_f32_16x16x32_bf16 v[74:77], v[122:125], v[162:165], v[74:77]
	v_mfma_f32_16x16x32_bf16 v[70:73], v[118:121], v[162:165], v[70:73]
	v_mfma_f32_16x16x32_bf16 v[62:65], v[114:117], v[162:165], v[62:65]
	v_mfma_f32_16x16x32_bf16 v[46:49], v[110:113], v[162:165], v[46:49]
	v_mfma_f32_16x16x32_bf16 v[42:45], v[106:109], v[162:165], v[42:45]
	v_mfma_f32_16x16x32_bf16 v[38:41], v[102:105], v[162:165], v[38:41]
	v_mfma_f32_16x16x32_bf16 v[34:37], v[98:101], v[162:165], v[34:37]

.LBB0_284:
	v_max3_f32 v130, v138, v140, v139
	v_max3_f32 v131, v141, v144, v145
	v_max_f32_e32 v132, v143, v142
	v_max3_f32 v130, v130, v131, v132
	ds_bpermute_b32 v131, v171, v130
	s_waitcnt lgkmcnt(0)
	v_max_f32_e32 v130, v130, v131
	ds_bpermute_b32 v131, v199, v130
	s_waitcnt lgkmcnt(0)
	v_max3_f32 v135, v185, v130, v131
	v_sub_f32_e32 v134, v141, v135
	v_mul_f32_e32 v134, 0x3fb8aa3b, v134
	v_exp_f32_e32 v136, v134
	v_sub_f32_e32 v134, v139, v135
	v_mul_f32_e32 v134, 0x3fb8aa3b, v134
	v_sub_f32_e32 v131, v140, v135
	v_exp_f32_e32 v137, v134
	v_sub_f32_e32 v134, v143, v135
	v_mul_f32_e32 v131, 0x3fb8aa3b, v131
	v_sub_f32_e32 v133, v138, v135
	v_mul_f32_e32 v134, 0x3fb8aa3b, v134
	v_exp_f32_e32 v131, v131
	v_mul_f32_e32 v133, 0x3fb8aa3b, v133
	v_exp_f32_e32 v138, v134
	v_sub_f32_e32 v134, v142, v135
	v_exp_f32_e32 v133, v133
	v_mul_f32_e32 v134, 0x3fb8aa3b, v134
	v_exp_f32_e32 v139, v134
	v_sub_f32_e32 v134, v145, v135
	v_mul_f32_e32 v134, 0x3fb8aa3b, v134
	v_sub_f32_e32 v130, v185, v135
	v_add_f32_e32 v132, 0, v131
	v_exp_f32_e32 v140, v134
	v_sub_f32_e32 v134, v144, v135
	v_mul_f32_e32 v130, 0x3fb8aa3b, v130
	v_add_f32_e32 v132, v133, v132
	v_mul_f32_e32 v134, 0x3fb8aa3b, v134
	v_add_f32_e32 v132, v136, v132
	v_exp_f32_e32 v141, v134
	v_exp_f32_e32 v134, v130
	v_add_f32_e32 v132, v137, v132
	v_add_f32_e32 v132, v138, v132
	v_add_f32_e32 v132, v139, v132
	v_add_f32_e32 v132, v140, v132
	v_pk_mul_f32 v[32:33], v[32:33], v[134:135] op_sel_hi:[1,0]
	v_pk_mul_f32 v[30:31], v[30:31], v[134:135] op_sel_hi:[1,0]
	v_pk_mul_f32 v[28:29], v[28:29], v[134:135] op_sel_hi:[1,0]
	v_pk_mul_f32 v[26:27], v[26:27], v[134:135] op_sel_hi:[1,0]
	v_pk_mul_f32 v[24:25], v[24:25], v[134:135] op_sel_hi:[1,0]
	v_pk_mul_f32 v[22:23], v[22:23], v[134:135] op_sel_hi:[1,0]
	v_pk_mul_f32 v[20:21], v[20:21], v[134:135] op_sel_hi:[1,0]
	v_pk_mul_f32 v[18:19], v[18:19], v[134:135] op_sel_hi:[1,0]
	v_pk_mul_f32 v[16:17], v[16:17], v[134:135] op_sel_hi:[1,0]
	v_pk_mul_f32 v[14:15], v[14:15], v[134:135] op_sel_hi:[1,0]
	v_pk_mul_f32 v[12:13], v[12:13], v[134:135] op_sel_hi:[1,0]
	v_pk_mul_f32 v[10:11], v[10:11], v[134:135] op_sel_hi:[1,0]
	v_pk_mul_f32 v[8:9], v[8:9], v[134:135] op_sel_hi:[1,0]
	v_pk_mul_f32 v[6:7], v[6:7], v[134:135] op_sel_hi:[1,0]
	v_pk_mul_f32 v[4:5], v[4:5], v[134:135] op_sel_hi:[1,0]
	v_pk_mul_f32 v[2:3], v[2:3], v[134:135] op_sel_hi:[1,0]
	v_add_f32_e32 v142, v141, v132
	v_cvt_pk_bf16_f32 v130, v131, v133
	v_cvt_pk_bf16_f32 v131, v136, v137
	v_cvt_pk_bf16_f32 v132, v138, v139
	v_cvt_pk_bf16_f32 v133, v140, v141
	v_fmac_f32_e32 v142, v175, v134
	v_mfma_f32_16x16x32_bf16 v[30:33], v[126:129], v[130:133], v[30:33]
	v_mov_b32_e32 v175, v142
	v_mov_b32_e32 v185, v135
	v_mfma_f32_16x16x32_bf16 v[26:29], v[122:125], v[130:133], v[26:29]
	v_mfma_f32_16x16x32_bf16 v[22:25], v[118:121], v[130:133], v[22:25]
	v_mfma_f32_16x16x32_bf16 v[18:21], v[114:117], v[130:133], v[18:21]
	v_mfma_f32_16x16x32_bf16 v[14:17], v[110:113], v[130:133], v[14:17]
	v_mfma_f32_16x16x32_bf16 v[10:13], v[106:109], v[130:133], v[10:13]
	v_mfma_f32_16x16x32_bf16 v[6:9], v[102:105], v[130:133], v[6:9]
	v_mfma_f32_16x16x32_bf16 v[2:5], v[98:101], v[130:133], v[2:5]
